# prep token loop: read-ahead + interleaved log-sigmoid chains extended to token 1 (tokens 1..14)
# speedup vs baseline: 1.0038x; 1.0038x over previous
.LBB0_225:
	s_ashr_i32 s0, s58, 3
	s_mul_hi_i32 s1, s0, 0x38e38e39
	s_lshr_b32 s4, s1, 31
	s_ashr_i32 s1, s1, 3
	s_add_i32 s1, s1, s4
	s_mul_i32 s4, s1, 36
	s_sub_i32 s21, s0, s4
	s_lshl_b32 s0, s21, 6
	s_mul_hi_i32 s4, s1, 0x900
	s_mulk_i32 s1, 0x900
	s_ashr_i32 s5, s0, 31
	s_add_u32 s0, s1, s0
	s_addc_u32 s1, s4, s5
	v_lshl_add_u64 v[10:11], s[0:1], 0, v[28:29]
	s_and_b32 s4, s44, 0x180
	v_lshlrev_b64 v[2:3], 11, v[10:11]
	v_lshl_add_u64 v[2:3], s[46:47], 0, v[2:3]
	s_lshl_b32 s92, s4, 1
	v_lshl_add_u64 v[2:3], v[2:3], 0, s[92:93]
	v_lshl_add_u64 v[6:7], v[2:3], 0, v[0:1]
	s_waitcnt lgkmcnt(0)
	s_barrier
	global_load_dwordx4 v[200:203], v[6:7], off
	s_nop 0
	global_load_dwordx4 v[204:207], v[6:7], off offset:1024
	v_lshl_add_u64 v[12:13], s[0:1], 0, v[30:31]
	v_lshl_add_u64 v[14:15], s[0:1], 0, v[32:33]
	v_lshl_add_u64 v[16:17], s[0:1], 0, v[34:35]
	v_lshlrev_b64 v[2:3], 11, v[12:13]
	v_lshl_add_u64 v[2:3], s[46:47], 0, v[2:3]
	v_lshl_add_u64 v[2:3], v[2:3], 0, s[92:93]
	v_lshl_add_u64 v[2:3], v[2:3], 0, v[0:1]
	global_load_dwordx4 v[208:211], v[2:3], off
	global_load_dwordx4 v[212:215], v[2:3], off offset:1024
	v_lshlrev_b64 v[2:3], 11, v[14:15]
	v_lshl_add_u64 v[2:3], s[46:47], 0, v[2:3]
	v_lshl_add_u64 v[2:3], v[2:3], 0, s[92:93]
	v_lshl_add_u64 v[2:3], v[2:3], 0, v[0:1]
	global_load_dwordx4 v[216:219], v[2:3], off
	global_load_dwordx4 v[220:223], v[2:3], off offset:1024
	v_lshlrev_b64 v[2:3], 11, v[16:17]
	v_lshl_add_u64 v[2:3], s[46:47], 0, v[2:3]
	v_lshl_add_u64 v[2:3], v[2:3], 0, s[92:93]
	v_lshl_add_u64 v[2:3], v[2:3], 0, v[0:1]
	global_load_dwordx4 v[224:227], v[2:3], off
	global_load_dwordx4 v[228:231], v[2:3], off offset:1024
	s_and_b32 s90, s58, 1
	s_or_b32 s88, s90, s2
	s_ashr_i32 s89, s88, 31
	v_readlane_b32 s60, v253, 20
	s_lshl_b64 s[0:1], s[88:89], 15
	v_readlane_b32 s66, v253, 26
	v_readlane_b32 s67, v253, 27
	v_readlane_b32 s68, v253, 28
	v_readlane_b32 s69, v253, 29
	v_readlane_b32 s61, v253, 21
	v_readlane_b32 s62, v253, 22
	v_readlane_b32 s63, v253, 23
	v_readlane_b32 s64, v253, 24
	v_readlane_b32 s65, v253, 25
	v_readlane_b32 s70, v253, 30
	v_readlane_b32 s71, v253, 31
	v_readlane_b32 s72, v253, 32
	v_readlane_b32 s73, v253, 33
	v_readlane_b32 s74, v253, 34
	v_readlane_b32 s75, v253, 35
	s_lshl_b32 s92, s90, 5
	s_add_u32 s0, s66, s0
	s_addc_u32 s1, s67, s1
	s_lshl_b32 s5, s4, 2
	s_add_u32 s0, s0, s5
	s_addc_u32 s1, s1, 0
	v_lshl_add_u64 v[2:3], v[24:25], 0, s[92:93]
	v_lshlrev_b64 v[4:5], 6, v[10:11]
	v_lshl_add_u64 v[4:5], v[2:3], 0, v[4:5]
	global_load_ushort v232, v[4:5], off
	v_lshlrev_b64 v[4:5], 6, v[12:13]
	v_lshl_add_u64 v[4:5], v[2:3], 0, v[4:5]
	global_load_ushort v233, v[4:5], off
	v_lshlrev_b64 v[4:5], 6, v[14:15]
	v_lshl_add_u64 v[4:5], v[2:3], 0, v[4:5]
	global_load_ushort v234, v[4:5], off
	v_lshlrev_b64 v[4:5], 6, v[16:17]
	v_lshl_add_u64 v[2:3], v[2:3], 0, v[4:5]
	global_load_ushort v235, v[2:3], off
	v_mov_b32_e32 v3, v1
	v_lshlrev_b32_e32 v2, 2, v20
	v_lshl_add_u64 v[4:5], s[0:1], 0, v[2:3]
	global_load_dword v60, v2, s[0:1]
	global_load_dword v61, v2, s[0:1] offset:256
	global_load_dword v62, v2, s[0:1] offset:2048
	global_load_dword v63, v2, s[0:1] offset:2304
	v_add_co_u32_e64 v2, s[0:1], s85, v4
	s_nop 1
	v_addc_co_u32_e64 v3, s[0:1], 0, v5, s[0:1]
	v_add_co_u32_e64 v6, s[0:1], s37, v4
	s_nop 1
	v_addc_co_u32_e64 v7, s[0:1], 0, v5, s[0:1]
	global_load_dword v64, v[6:7], off offset:-4096
	global_load_dword v65, v[2:3], off offset:256
	global_load_dword v66, v[2:3], off offset:2048
	global_load_dword v67, v[2:3], off offset:2304
	global_load_dword v47, v[6:7], off
	global_load_dword v46, v[6:7], off offset:256
	global_load_dword v17, v[6:7], off offset:2048
	global_load_dword v16, v[6:7], off offset:2304
	v_add_co_u32_e64 v2, s[0:1], s33, v4
	s_nop 1
	v_addc_co_u32_e64 v3, s[0:1], 0, v5, s[0:1]
	s_movk_i32 s0, 0x4000
	s_nop 0
	v_add_co_u32_e64 v6, s[0:1], s0, v4
	s_nop 1
	v_addc_co_u32_e64 v7, s[0:1], 0, v5, s[0:1]
	s_movk_i32 s0, 0x5000
	global_load_dword v52, v[6:7], off offset:-4096
	global_load_dword v53, v[2:3], off offset:256
	global_load_dword v54, v[2:3], off offset:2048
	global_load_dword v55, v[2:3], off offset:2304
	global_load_dword v48, v[6:7], off
	global_load_dword v49, v[6:7], off offset:256
	global_load_dword v50, v[6:7], off offset:2048
	global_load_dword v51, v[6:7], off offset:2304
	v_add_co_u32_e64 v2, s[0:1], s0, v4
	s_nop 1
	v_addc_co_u32_e64 v3, s[0:1], 0, v5, s[0:1]
	s_movk_i32 s0, 0x6000
	s_nop 0
	v_add_co_u32_e64 v8, s[0:1], s0, v4
	s_nop 1
	v_addc_co_u32_e64 v9, s[0:1], 0, v5, s[0:1]
	s_movk_i32 s0, 0x7000
	global_load_dword v56, v[8:9], off offset:-4096
	global_load_dword v57, v[2:3], off offset:256
	global_load_dword v58, v[2:3], off offset:2048
	global_load_dword v59, v[2:3], off offset:2304
	global_load_dword v12, v[8:9], off
	global_load_dword v13, v[8:9], off offset:256
	global_load_dword v6, v[8:9], off offset:2048
	global_load_dword v7, v[8:9], off offset:2304
	v_add_co_u32_e64 v2, s[0:1], s0, v4
	s_nop 1
	v_addc_co_u32_e64 v3, s[0:1], 0, v5, s[0:1]
	s_lshl_b32 s0, s88, 9
	s_or_b32 s0, s0, s4
	global_load_dword v14, v[2:3], off
	global_load_dword v15, v[2:3], off offset:256
	global_load_dword v9, v[2:3], off offset:2048
	global_load_dword v10, v[2:3], off offset:2304
	v_or_b32_e32 v2, s0, v20
	v_ashrrev_i32_e32 v3, 31, v2
	v_lshl_add_u64 v[2:3], v[2:3], 2, s[68:69]
	global_load_dword v69, v[2:3], off
	global_load_dword v68, v[2:3], off offset:256
	s_waitcnt vmcnt(34)
	ds_write_b128 v82, v[200:203]
	ds_write_b128 v82, v[204:207] offset:16384
	ds_write_b128 v85, v[208:211]
	ds_write_b128 v85, v[212:215] offset:16384
	ds_write_b128 v88, v[216:219]
	ds_write_b128 v88, v[220:223] offset:16384
	ds_write_b128 v91, v[224:227]
	ds_write_b128 v91, v[228:231] offset:16384
	v_lshlrev_b32_e32 v236, 16, v232
	v_lshlrev_b32_e32 v237, 16, v233
	ds_write2st64_b32 v18, v236, v237 offset0:128 offset1:132
	v_lshlrev_b32_e32 v238, 16, v234
	v_lshlrev_b32_e32 v239, 16, v235
	ds_write2st64_b32 v18, v238, v239 offset0:136 offset1:140
	s_waitcnt lgkmcnt(0)
	s_barrier
	ds_read_b128 v[2:5], v19 offset:32768
	ds_read_b128 v[156:159], v19 offset:32784
	ds_read_b128 v[160:163], v19 offset:32800
	ds_read_b128 v[164:167], v19 offset:32816
	s_waitcnt vmcnt(1) lgkmcnt(3)
	v_fma_f32 v8, v60, v2, v69
	v_fmac_f32_e32 v8, v62, v3
	v_fmac_f32_e32 v8, v64, v4
	v_fmac_f32_e32 v8, v66, v5
	s_waitcnt lgkmcnt(2)
	v_fmac_f32_e32 v8, v47, v156
	v_fmac_f32_e32 v8, v17, v157
	v_fmac_f32_e32 v8, v52, v158
	v_fmac_f32_e32 v8, v54, v159
	s_waitcnt lgkmcnt(1)
	v_fmac_f32_e32 v8, v48, v160
	v_fmac_f32_e32 v8, v50, v161
	v_fmac_f32_e32 v8, v56, v162
	v_fmac_f32_e32 v8, v58, v163
	s_waitcnt lgkmcnt(0)
	v_fmac_f32_e32 v8, v12, v164
	v_fmac_f32_e32 v8, v6, v165
	s_waitcnt vmcnt(0)
	v_fma_f32 v2, v61, v2, v68
	v_fmac_f32_e32 v8, v14, v166
	v_fmac_f32_e32 v2, v63, v3
	v_fmac_f32_e32 v8, v9, v167
	v_fmac_f32_e32 v2, v65, v4
	v_mul_f32_e64 v4, |v8|, s84
	v_exp_f32_e32 v4, v4
	v_fmac_f32_e32 v2, v67, v5
	v_fmac_f32_e32 v2, v46, v156
	v_fmac_f32_e32 v2, v16, v157
	v_add_f32_e32 v4, 1.0, v4
	v_cmp_gt_f32_e64 s[0:1], s31, v4
	v_fmac_f32_e32 v2, v53, v158
	v_fmac_f32_e32 v2, v55, v159
	v_cndmask_b32_e64 v5, 0, 32, s[0:1]
	v_ldexp_f32 v4, v4, v5
	v_log_f32_e32 v4, v4
	v_fmac_f32_e32 v2, v49, v160
	v_fmac_f32_e32 v2, v51, v161
	v_fmac_f32_e32 v2, v57, v162
	v_mul_f32_e32 v5, 0x3f317217, v4
	v_fmac_f32_e32 v2, v59, v163
	v_fma_f32 v5, v4, s78, -v5
	v_fmac_f32_e32 v2, v13, v164
	v_fmac_f32_e32 v5, 0x3377d1cf, v4
	v_fmac_f32_e32 v2, v7, v165
	v_fmac_f32_e32 v5, 0x3f317217, v4
	v_cmp_lt_f32_e64 s[88:89], |v4|, s79
	v_fmac_f32_e32 v2, v15, v166
	v_fmac_f32_e32 v2, v10, v167
	v_cndmask_b32_e64 v4, v4, v5, s[88:89]
	v_cndmask_b32_e64 v5, 0, v198, s[0:1]
	v_min_f32_e32 v3, 0, v8
	v_sub_f32_e32 v4, v4, v5
	v_sub_f32_e32 v70, v3, v4
	v_min_f32_e32 v3, 0, v2
	v_mul_f32_e64 v2, |v2|, s84
	v_exp_f32_e32 v2, v2
	v_fma_f32 v11, v70, s10, 0
	v_add_f32_e32 v2, 1.0, v2
	v_cmp_gt_f32_e64 s[0:1], s31, v2
	s_nop 1
	v_cndmask_b32_e64 v4, 0, 32, s[0:1]
	v_ldexp_f32 v2, v2, v4
	v_log_f32_e32 v2, v2
	s_nop 0
	v_mul_f32_e32 v4, 0x3f317217, v2
	v_fma_f32 v4, v2, s78, -v4
	v_fmac_f32_e32 v4, 0x3377d1cf, v2
	v_fmac_f32_e32 v4, 0x3f317217, v2
	v_cmp_lt_f32_e64 s[88:89], |v2|, s79
	s_nop 1
	v_cndmask_b32_e64 v2, v2, v4, s[88:89]
	v_cndmask_b32_e64 v4, 0, v198, s[0:1]
	v_sub_f32_e32 v2, v2, v4
	v_sub_f32_e32 v71, v3, v2
	ds_read_b128 v[2:5], v19 offset:32832
	ds_read_b128 v[234:237], v19 offset:32848
	ds_read_b128 v[238:241], v19 offset:32864
	ds_read_b128 v[244:247], v19 offset:32880
	v_fma_f32 v8, v71, s10, 0
	s_waitcnt lgkmcnt(3)
	v_fma_f32 v155, v60, v2, v69
	v_fma_f32 v156, v61, v2, v68
	v_fmac_f32_e32 v155, v62, v3
	v_fmac_f32_e32 v156, v63, v3
	v_fmac_f32_e32 v155, v64, v4
	v_fmac_f32_e32 v156, v65, v4
	v_fmac_f32_e32 v155, v66, v5
	v_fmac_f32_e32 v156, v67, v5
	s_waitcnt lgkmcnt(2)
	v_fmac_f32_e32 v155, v47, v234
	v_fmac_f32_e32 v156, v46, v234
	v_fmac_f32_e32 v155, v17, v235
	v_fmac_f32_e32 v156, v16, v235
	v_fmac_f32_e32 v155, v52, v236
	v_fmac_f32_e32 v156, v53, v236
	v_fmac_f32_e32 v155, v54, v237
	v_fmac_f32_e32 v156, v55, v237
	s_waitcnt lgkmcnt(1)
	v_fmac_f32_e32 v155, v48, v238
	v_fmac_f32_e32 v156, v49, v238
	v_fmac_f32_e32 v155, v50, v239
	v_fmac_f32_e32 v156, v51, v239
	v_fmac_f32_e32 v155, v56, v240
	v_fmac_f32_e32 v156, v57, v240
	v_fmac_f32_e32 v155, v58, v241
	v_fmac_f32_e32 v156, v59, v241
	s_waitcnt lgkmcnt(0)
	v_fmac_f32_e32 v155, v12, v244
	v_fmac_f32_e32 v156, v13, v244
	v_fmac_f32_e32 v155, v6, v245
	v_fmac_f32_e32 v156, v7, v245
	v_fmac_f32_e32 v155, v14, v246
	v_fmac_f32_e32 v156, v15, v246
	v_fmac_f32_e32 v155, v9, v247
	v_fmac_f32_e32 v156, v10, v247
	ds_read_b128 v[2:5], v19 offset:32896
	ds_read_b128 v[234:237], v19 offset:32912
	ds_read_b128 v[238:241], v19 offset:32928
	ds_read_b128 v[244:247], v19 offset:32944
	v_mul_f32_e64 v249, |v155|, s84
	v_mul_f32_e64 v231, |v156|, s84
	v_exp_f32_e32 v249, v249
	v_exp_f32_e32 v231, v231
	v_min_f32_e32 v248, 0, v155
	v_min_f32_e32 v230, 0, v156
	v_add_f32_e32 v249, 1.0, v249
	v_add_f32_e32 v231, 1.0, v231
	v_cmp_gt_f32_e64 s[0:1], s31, v249
	v_cmp_gt_f32_e64 s[100:101], s31, v231
	s_nop 0
	v_cndmask_b32_e64 v250, 0, 32, s[0:1]
	v_cndmask_b32_e64 v232, 0, 32, s[100:101]
	v_ldexp_f32 v249, v249, v250
	v_ldexp_f32 v231, v231, v232
	v_log_f32_e32 v249, v249
	v_log_f32_e32 v231, v231
	v_mul_f32_e32 v250, 0x3f317217, v249
	v_mul_f32_e32 v232, 0x3f317217, v231
	v_fma_f32 v250, v249, s78, -v250
	v_fma_f32 v232, v231, s78, -v232
	v_fmac_f32_e32 v250, 0x3377d1cf, v249
	v_fmac_f32_e32 v232, 0x3377d1cf, v231
	v_fmac_f32_e32 v250, 0x3f317217, v249
	v_fmac_f32_e32 v232, 0x3f317217, v231
	v_cmp_lt_f32_e64 s[88:89], |v249|, s79
	v_cndmask_b32_e64 v251, 0, v198, s[0:1]
	v_cndmask_b32_e64 v233, 0, v198, s[100:101]
	v_cndmask_b32_e64 v249, v249, v250, s[88:89]
	v_cmp_lt_f32_e64 s[88:89], |v231|, s79
	v_sub_f32_e32 v249, v249, v251
	v_sub_f32_e32 v159, v248, v249
	v_cndmask_b32_e64 v231, v231, v232, s[88:89]
	v_sub_f32_e32 v231, v231, v233
	v_sub_f32_e32 v160, v230, v231
	v_fmamk_f32 v156, v159, 0x3d800000, v11
	v_fmamk_f32 v155, v160, 0x3d800000, v8
	s_waitcnt lgkmcnt(3)
	v_fma_f32 v157, v60, v2, v69
	v_fma_f32 v158, v61, v2, v68
	v_fmac_f32_e32 v157, v62, v3
	v_fmac_f32_e32 v158, v63, v3
	v_fmac_f32_e32 v157, v64, v4
	v_fmac_f32_e32 v158, v65, v4
	v_fmac_f32_e32 v157, v66, v5
	v_fmac_f32_e32 v158, v67, v5
	s_waitcnt lgkmcnt(2)
	v_fmac_f32_e32 v157, v47, v234
	v_fmac_f32_e32 v158, v46, v234
	v_fmac_f32_e32 v157, v17, v235
	v_fmac_f32_e32 v158, v16, v235
	v_fmac_f32_e32 v157, v52, v236
	v_fmac_f32_e32 v158, v53, v236
	v_fmac_f32_e32 v157, v54, v237
	v_fmac_f32_e32 v158, v55, v237
	s_waitcnt lgkmcnt(1)
	v_fmac_f32_e32 v157, v48, v238
	v_fmac_f32_e32 v158, v49, v238
	v_fmac_f32_e32 v157, v50, v239
	v_fmac_f32_e32 v158, v51, v239
	v_fmac_f32_e32 v157, v56, v240
	v_fmac_f32_e32 v158, v57, v240
	v_fmac_f32_e32 v157, v58, v241
	v_fmac_f32_e32 v158, v59, v241
	s_waitcnt lgkmcnt(0)
	v_fmac_f32_e32 v157, v12, v244
	v_fmac_f32_e32 v158, v13, v244
	v_fmac_f32_e32 v157, v6, v245
	v_fmac_f32_e32 v158, v7, v245
	v_fmac_f32_e32 v157, v14, v246
	v_fmac_f32_e32 v158, v15, v246
	v_fmac_f32_e32 v157, v9, v247
	v_fmac_f32_e32 v158, v10, v247
	ds_read_b128 v[2:5], v19 offset:32960
	ds_read_b128 v[234:237], v19 offset:32976
	ds_read_b128 v[238:241], v19 offset:32992
	ds_read_b128 v[244:247], v19 offset:33008
	v_mul_f32_e64 v249, |v157|, s84
	v_mul_f32_e64 v231, |v158|, s84
	v_exp_f32_e32 v249, v249
	v_exp_f32_e32 v231, v231
	v_min_f32_e32 v248, 0, v157
	v_min_f32_e32 v230, 0, v158
	v_add_f32_e32 v249, 1.0, v249
	v_add_f32_e32 v231, 1.0, v231
	v_cmp_gt_f32_e64 s[0:1], s31, v249
	v_cmp_gt_f32_e64 s[100:101], s31, v231
	s_nop 0
	v_cndmask_b32_e64 v250, 0, 32, s[0:1]
	v_cndmask_b32_e64 v232, 0, 32, s[100:101]
	v_ldexp_f32 v249, v249, v250
	v_ldexp_f32 v231, v231, v232
	v_log_f32_e32 v249, v249
	v_log_f32_e32 v231, v231
	v_mul_f32_e32 v250, 0x3f317217, v249
	v_mul_f32_e32 v232, 0x3f317217, v231
	v_fma_f32 v250, v249, s78, -v250
	v_fma_f32 v232, v231, s78, -v232
	v_fmac_f32_e32 v250, 0x3377d1cf, v249
	v_fmac_f32_e32 v232, 0x3377d1cf, v231
	v_fmac_f32_e32 v250, 0x3f317217, v249
	v_fmac_f32_e32 v232, 0x3f317217, v231
	v_cmp_lt_f32_e64 s[88:89], |v249|, s79
	v_cndmask_b32_e64 v251, 0, v198, s[0:1]
	v_cndmask_b32_e64 v233, 0, v198, s[100:101]
	v_cndmask_b32_e64 v249, v249, v250, s[88:89]
	v_cmp_lt_f32_e64 s[88:89], |v231|, s79
	v_sub_f32_e32 v249, v249, v251
	v_sub_f32_e32 v163, v248, v249
	v_cndmask_b32_e64 v231, v231, v232, s[88:89]
	v_sub_f32_e32 v231, v231, v233
	v_sub_f32_e32 v164, v230, v231
	v_fmamk_f32 v158, v163, 0x3d800000, v156
	v_fmamk_f32 v157, v164, 0x3d800000, v155
	s_waitcnt lgkmcnt(3)
	v_fma_f32 v161, v60, v2, v69
	v_fma_f32 v162, v61, v2, v68
	v_fmac_f32_e32 v161, v62, v3
	v_fmac_f32_e32 v162, v63, v3
	v_fmac_f32_e32 v161, v64, v4
	v_fmac_f32_e32 v162, v65, v4
	v_fmac_f32_e32 v161, v66, v5
	v_fmac_f32_e32 v162, v67, v5
	s_waitcnt lgkmcnt(2)
	v_fmac_f32_e32 v161, v47, v234
	v_fmac_f32_e32 v162, v46, v234
	v_fmac_f32_e32 v161, v17, v235
	v_fmac_f32_e32 v162, v16, v235
	v_fmac_f32_e32 v161, v52, v236
	v_fmac_f32_e32 v162, v53, v236
	v_fmac_f32_e32 v161, v54, v237
	v_fmac_f32_e32 v162, v55, v237
	s_waitcnt lgkmcnt(1)
	v_fmac_f32_e32 v161, v48, v238
	v_fmac_f32_e32 v162, v49, v238
	v_fmac_f32_e32 v161, v50, v239
	v_fmac_f32_e32 v162, v51, v239
	v_fmac_f32_e32 v161, v56, v240
	v_fmac_f32_e32 v162, v57, v240
	v_fmac_f32_e32 v161, v58, v241
	v_fmac_f32_e32 v162, v59, v241
	s_waitcnt lgkmcnt(0)
	v_fmac_f32_e32 v161, v12, v244
	v_fmac_f32_e32 v162, v13, v244
	v_fmac_f32_e32 v161, v6, v245
	v_fmac_f32_e32 v162, v7, v245
	v_fmac_f32_e32 v161, v14, v246
	v_fmac_f32_e32 v162, v15, v246
	v_fmac_f32_e32 v161, v9, v247
	v_fmac_f32_e32 v162, v10, v247
	ds_read_b128 v[2:5], v19 offset:33024
	ds_read_b128 v[234:237], v19 offset:33040
	ds_read_b128 v[238:241], v19 offset:33056
	ds_read_b128 v[244:247], v19 offset:33072
	v_mul_f32_e64 v249, |v161|, s84
	v_mul_f32_e64 v231, |v162|, s84
	v_exp_f32_e32 v249, v249
	v_exp_f32_e32 v231, v231
	v_min_f32_e32 v248, 0, v161
	v_min_f32_e32 v230, 0, v162
	v_add_f32_e32 v249, 1.0, v249
	v_add_f32_e32 v231, 1.0, v231
	v_cmp_gt_f32_e64 s[0:1], s31, v249
	v_cmp_gt_f32_e64 s[100:101], s31, v231
	s_nop 0
	v_cndmask_b32_e64 v250, 0, 32, s[0:1]
	v_cndmask_b32_e64 v232, 0, 32, s[100:101]
	v_ldexp_f32 v249, v249, v250
	v_ldexp_f32 v231, v231, v232
	v_log_f32_e32 v249, v249
	v_log_f32_e32 v231, v231
	v_mul_f32_e32 v250, 0x3f317217, v249
	v_mul_f32_e32 v232, 0x3f317217, v231
	v_fma_f32 v250, v249, s78, -v250
	v_fma_f32 v232, v231, s78, -v232
	v_fmac_f32_e32 v250, 0x3377d1cf, v249
	v_fmac_f32_e32 v232, 0x3377d1cf, v231
	v_fmac_f32_e32 v250, 0x3f317217, v249
	v_fmac_f32_e32 v232, 0x3f317217, v231
	v_cmp_lt_f32_e64 s[88:89], |v249|, s79
	v_cndmask_b32_e64 v251, 0, v198, s[0:1]
	v_cndmask_b32_e64 v233, 0, v198, s[100:101]
	v_cndmask_b32_e64 v249, v249, v250, s[88:89]
	v_cmp_lt_f32_e64 s[88:89], |v231|, s79
	v_sub_f32_e32 v249, v249, v251
	v_sub_f32_e32 v165, v248, v249
	v_cndmask_b32_e64 v231, v231, v232, s[88:89]
	v_sub_f32_e32 v231, v231, v233
	v_sub_f32_e32 v166, v230, v231
	v_fmamk_f32 v162, v165, 0x3d800000, v158
	v_fmamk_f32 v161, v166, 0x3d800000, v157
	s_waitcnt lgkmcnt(3)
	v_fma_f32 v168, v60, v2, v69
	v_fma_f32 v167, v61, v2, v68
	v_fmac_f32_e32 v168, v62, v3
	v_fmac_f32_e32 v167, v63, v3
	v_fmac_f32_e32 v168, v64, v4
	v_fmac_f32_e32 v167, v65, v4
	v_fmac_f32_e32 v168, v66, v5
	v_fmac_f32_e32 v167, v67, v5
	s_waitcnt lgkmcnt(2)
	v_fmac_f32_e32 v168, v47, v234
	v_fmac_f32_e32 v167, v46, v234
	v_fmac_f32_e32 v168, v17, v235
	v_fmac_f32_e32 v167, v16, v235
	v_fmac_f32_e32 v168, v52, v236
	v_fmac_f32_e32 v167, v53, v236
	v_fmac_f32_e32 v168, v54, v237
	v_fmac_f32_e32 v167, v55, v237
	s_waitcnt lgkmcnt(1)
	v_fmac_f32_e32 v168, v48, v238
	v_fmac_f32_e32 v167, v49, v238
	v_fmac_f32_e32 v168, v50, v239
	v_fmac_f32_e32 v167, v51, v239
	v_fmac_f32_e32 v168, v56, v240
	v_fmac_f32_e32 v167, v57, v240
	v_fmac_f32_e32 v168, v58, v241
	v_fmac_f32_e32 v167, v59, v241
	s_waitcnt lgkmcnt(0)
	v_fmac_f32_e32 v168, v12, v244
	v_fmac_f32_e32 v167, v13, v244
	v_fmac_f32_e32 v168, v6, v245
	v_fmac_f32_e32 v167, v7, v245
	v_fmac_f32_e32 v168, v14, v246
	v_fmac_f32_e32 v167, v15, v246
	v_fmac_f32_e32 v168, v9, v247
	v_fmac_f32_e32 v167, v10, v247
	ds_read_b128 v[2:5], v19 offset:33088
	ds_read_b128 v[234:237], v19 offset:33104
	ds_read_b128 v[238:241], v19 offset:33120
	ds_read_b128 v[244:247], v19 offset:33136
	v_mul_f32_e64 v249, |v168|, s84
	v_mul_f32_e64 v231, |v167|, s84
	v_exp_f32_e32 v249, v249
	v_exp_f32_e32 v231, v231
	v_min_f32_e32 v248, 0, v168
	v_min_f32_e32 v230, 0, v167
	v_add_f32_e32 v249, 1.0, v249
	v_add_f32_e32 v231, 1.0, v231
	v_cmp_gt_f32_e64 s[0:1], s31, v249
	v_cmp_gt_f32_e64 s[100:101], s31, v231
	s_nop 0
	v_cndmask_b32_e64 v250, 0, 32, s[0:1]
	v_cndmask_b32_e64 v232, 0, 32, s[100:101]
	v_ldexp_f32 v249, v249, v250
	v_ldexp_f32 v231, v231, v232
	v_log_f32_e32 v249, v249
	v_log_f32_e32 v231, v231
	v_mul_f32_e32 v250, 0x3f317217, v249
	v_mul_f32_e32 v232, 0x3f317217, v231
	v_fma_f32 v250, v249, s78, -v250
	v_fma_f32 v232, v231, s78, -v232
	v_fmac_f32_e32 v250, 0x3377d1cf, v249
	v_fmac_f32_e32 v232, 0x3377d1cf, v231
	v_fmac_f32_e32 v250, 0x3f317217, v249
	v_fmac_f32_e32 v232, 0x3f317217, v231
	v_cmp_lt_f32_e64 s[88:89], |v249|, s79
	v_cndmask_b32_e64 v251, 0, v198, s[0:1]
	v_cndmask_b32_e64 v233, 0, v198, s[100:101]
	v_cndmask_b32_e64 v249, v249, v250, s[88:89]
	v_cmp_lt_f32_e64 s[88:89], |v231|, s79
	v_sub_f32_e32 v249, v249, v251
	v_sub_f32_e32 v171, v248, v249
	v_cndmask_b32_e64 v231, v231, v232, s[88:89]
	v_sub_f32_e32 v231, v231, v233
	v_sub_f32_e32 v174, v230, v231
	v_fmamk_f32 v168, v171, 0x3d800000, v162
	v_fmamk_f32 v167, v174, 0x3d800000, v161
	s_waitcnt lgkmcnt(3)
	v_fma_f32 v169, v60, v2, v69
	v_fma_f32 v170, v61, v2, v68
	v_fmac_f32_e32 v169, v62, v3
	v_fmac_f32_e32 v170, v63, v3
	v_fmac_f32_e32 v169, v64, v4
	v_fmac_f32_e32 v170, v65, v4
	v_fmac_f32_e32 v169, v66, v5
	v_fmac_f32_e32 v170, v67, v5
	s_waitcnt lgkmcnt(2)
	v_fmac_f32_e32 v169, v47, v234
	v_fmac_f32_e32 v170, v46, v234
	v_fmac_f32_e32 v169, v17, v235
	v_fmac_f32_e32 v170, v16, v235
	v_fmac_f32_e32 v169, v52, v236
	v_fmac_f32_e32 v170, v53, v236
	v_fmac_f32_e32 v169, v54, v237
	v_fmac_f32_e32 v170, v55, v237
	s_waitcnt lgkmcnt(1)
	v_fmac_f32_e32 v169, v48, v238
	v_fmac_f32_e32 v170, v49, v238
	v_fmac_f32_e32 v169, v50, v239
	v_fmac_f32_e32 v170, v51, v239
	v_fmac_f32_e32 v169, v56, v240
	v_fmac_f32_e32 v170, v57, v240
	v_fmac_f32_e32 v169, v58, v241
	v_fmac_f32_e32 v170, v59, v241
	s_waitcnt lgkmcnt(0)
	v_fmac_f32_e32 v169, v12, v244
	v_fmac_f32_e32 v170, v13, v244
	v_fmac_f32_e32 v169, v6, v245
	v_fmac_f32_e32 v170, v7, v245
	v_fmac_f32_e32 v169, v14, v246
	v_fmac_f32_e32 v170, v15, v246
	v_fmac_f32_e32 v169, v9, v247
	v_fmac_f32_e32 v170, v10, v247
	ds_read_b128 v[2:5], v19 offset:33152
	ds_read_b128 v[234:237], v19 offset:33168
	ds_read_b128 v[238:241], v19 offset:33184
	ds_read_b128 v[244:247], v19 offset:33200
	v_mul_f32_e64 v249, |v169|, s84
	v_mul_f32_e64 v231, |v170|, s84
	v_exp_f32_e32 v249, v249
	v_exp_f32_e32 v231, v231
	v_min_f32_e32 v248, 0, v169
	v_min_f32_e32 v230, 0, v170
	v_add_f32_e32 v249, 1.0, v249
	v_add_f32_e32 v231, 1.0, v231
	v_cmp_gt_f32_e64 s[0:1], s31, v249
	v_cmp_gt_f32_e64 s[100:101], s31, v231
	s_nop 0
	v_cndmask_b32_e64 v250, 0, 32, s[0:1]
	v_cndmask_b32_e64 v232, 0, 32, s[100:101]
	v_ldexp_f32 v249, v249, v250
	v_ldexp_f32 v231, v231, v232
	v_log_f32_e32 v249, v249
	v_log_f32_e32 v231, v231
	v_mul_f32_e32 v250, 0x3f317217, v249
	v_mul_f32_e32 v232, 0x3f317217, v231
	v_fma_f32 v250, v249, s78, -v250
	v_fma_f32 v232, v231, s78, -v232
	v_fmac_f32_e32 v250, 0x3377d1cf, v249
	v_fmac_f32_e32 v232, 0x3377d1cf, v231
	v_fmac_f32_e32 v250, 0x3f317217, v249
	v_fmac_f32_e32 v232, 0x3f317217, v231
	v_cmp_lt_f32_e64 s[88:89], |v249|, s79
	v_cndmask_b32_e64 v251, 0, v198, s[0:1]
	v_cndmask_b32_e64 v233, 0, v198, s[100:101]
	v_cndmask_b32_e64 v249, v249, v250, s[88:89]
	v_cmp_lt_f32_e64 s[88:89], |v231|, s79
	v_sub_f32_e32 v249, v249, v251
	v_sub_f32_e32 v177, v248, v249
	v_cndmask_b32_e64 v231, v231, v232, s[88:89]
	v_sub_f32_e32 v231, v231, v233
	v_sub_f32_e32 v180, v230, v231
	v_fmamk_f32 v170, v177, 0x3d800000, v168
	v_fmamk_f32 v169, v180, 0x3d800000, v167
	s_waitcnt lgkmcnt(3)
	v_fma_f32 v172, v60, v2, v69
	v_fma_f32 v173, v61, v2, v68
	v_fmac_f32_e32 v172, v62, v3
	v_fmac_f32_e32 v173, v63, v3
	v_fmac_f32_e32 v172, v64, v4
	v_fmac_f32_e32 v173, v65, v4
	v_fmac_f32_e32 v172, v66, v5
	v_fmac_f32_e32 v173, v67, v5
	s_waitcnt lgkmcnt(2)
	v_fmac_f32_e32 v172, v47, v234
	v_fmac_f32_e32 v173, v46, v234
	v_fmac_f32_e32 v172, v17, v235
	v_fmac_f32_e32 v173, v16, v235
	v_fmac_f32_e32 v172, v52, v236
	v_fmac_f32_e32 v173, v53, v236
	v_fmac_f32_e32 v172, v54, v237
	v_fmac_f32_e32 v173, v55, v237
	s_waitcnt lgkmcnt(1)
	v_fmac_f32_e32 v172, v48, v238
	v_fmac_f32_e32 v173, v49, v238
	v_fmac_f32_e32 v172, v50, v239
	v_fmac_f32_e32 v173, v51, v239
	v_fmac_f32_e32 v172, v56, v240
	v_fmac_f32_e32 v173, v57, v240
	v_fmac_f32_e32 v172, v58, v241
	v_fmac_f32_e32 v173, v59, v241
	s_waitcnt lgkmcnt(0)
	v_fmac_f32_e32 v172, v12, v244
	v_fmac_f32_e32 v173, v13, v244
	v_fmac_f32_e32 v172, v6, v245
	v_fmac_f32_e32 v173, v7, v245
	v_fmac_f32_e32 v172, v14, v246
	v_fmac_f32_e32 v173, v15, v246
	v_fmac_f32_e32 v172, v9, v247
	v_fmac_f32_e32 v173, v10, v247
	ds_read_b128 v[2:5], v19 offset:33216
	ds_read_b128 v[234:237], v19 offset:33232
	ds_read_b128 v[238:241], v19 offset:33248
	ds_read_b128 v[244:247], v19 offset:33264
	v_mul_f32_e64 v249, |v172|, s84
	v_mul_f32_e64 v231, |v173|, s84
	v_exp_f32_e32 v249, v249
	v_exp_f32_e32 v231, v231
	v_min_f32_e32 v248, 0, v172
	v_min_f32_e32 v230, 0, v173
	v_add_f32_e32 v249, 1.0, v249
	v_add_f32_e32 v231, 1.0, v231
	v_cmp_gt_f32_e64 s[0:1], s31, v249
	v_cmp_gt_f32_e64 s[100:101], s31, v231
	s_nop 0
	v_cndmask_b32_e64 v250, 0, 32, s[0:1]
	v_cndmask_b32_e64 v232, 0, 32, s[100:101]
	v_ldexp_f32 v249, v249, v250
	v_ldexp_f32 v231, v231, v232
	v_log_f32_e32 v249, v249
	v_log_f32_e32 v231, v231
	v_mul_f32_e32 v250, 0x3f317217, v249
	v_mul_f32_e32 v232, 0x3f317217, v231
	v_fma_f32 v250, v249, s78, -v250
	v_fma_f32 v232, v231, s78, -v232
	v_fmac_f32_e32 v250, 0x3377d1cf, v249
	v_fmac_f32_e32 v232, 0x3377d1cf, v231
	v_fmac_f32_e32 v250, 0x3f317217, v249
	v_fmac_f32_e32 v232, 0x3f317217, v231
	v_cmp_lt_f32_e64 s[88:89], |v249|, s79
	v_cndmask_b32_e64 v251, 0, v198, s[0:1]
	v_cndmask_b32_e64 v233, 0, v198, s[100:101]
	v_cndmask_b32_e64 v249, v249, v250, s[88:89]
	v_cmp_lt_f32_e64 s[88:89], |v231|, s79
	v_sub_f32_e32 v249, v249, v251
	v_sub_f32_e32 v183, v248, v249
	v_cndmask_b32_e64 v231, v231, v232, s[88:89]
	v_sub_f32_e32 v231, v231, v233
	v_sub_f32_e32 v199, v230, v231
	v_fmamk_f32 v173, v183, 0x3d800000, v170
	v_fmamk_f32 v172, v199, 0x3d800000, v169
	s_waitcnt lgkmcnt(3)
	v_fma_f32 v175, v60, v2, v69
	v_fma_f32 v176, v61, v2, v68
	v_fmac_f32_e32 v175, v62, v3
	v_fmac_f32_e32 v176, v63, v3
	v_fmac_f32_e32 v175, v64, v4
	v_fmac_f32_e32 v176, v65, v4
	v_fmac_f32_e32 v175, v66, v5
	v_fmac_f32_e32 v176, v67, v5
	s_waitcnt lgkmcnt(2)
	v_fmac_f32_e32 v175, v47, v234
	v_fmac_f32_e32 v176, v46, v234
	v_fmac_f32_e32 v175, v17, v235
	v_fmac_f32_e32 v176, v16, v235
	v_fmac_f32_e32 v175, v52, v236
	v_fmac_f32_e32 v176, v53, v236
	v_fmac_f32_e32 v175, v54, v237
	v_fmac_f32_e32 v176, v55, v237
	s_waitcnt lgkmcnt(1)
	v_fmac_f32_e32 v175, v48, v238
	v_fmac_f32_e32 v176, v49, v238
	v_fmac_f32_e32 v175, v50, v239
	v_fmac_f32_e32 v176, v51, v239
	v_fmac_f32_e32 v175, v56, v240
	v_fmac_f32_e32 v176, v57, v240
	v_fmac_f32_e32 v175, v58, v241
	v_fmac_f32_e32 v176, v59, v241
	s_waitcnt lgkmcnt(0)
	v_fmac_f32_e32 v175, v12, v244
	v_fmac_f32_e32 v176, v13, v244
	v_fmac_f32_e32 v175, v6, v245
	v_fmac_f32_e32 v176, v7, v245
	v_fmac_f32_e32 v175, v14, v246
	v_fmac_f32_e32 v176, v15, v246
	v_fmac_f32_e32 v175, v9, v247
	v_fmac_f32_e32 v176, v10, v247
	ds_read_b128 v[2:5], v19 offset:33280
	ds_read_b128 v[234:237], v19 offset:33296
	ds_read_b128 v[238:241], v19 offset:33312
	ds_read_b128 v[244:247], v19 offset:33328
	v_mul_f32_e64 v249, |v175|, s84
	v_mul_f32_e64 v231, |v176|, s84
	v_exp_f32_e32 v249, v249
	v_exp_f32_e32 v231, v231
	v_min_f32_e32 v248, 0, v175
	v_min_f32_e32 v230, 0, v176
	v_add_f32_e32 v249, 1.0, v249
	v_add_f32_e32 v231, 1.0, v231
	v_cmp_gt_f32_e64 s[0:1], s31, v249
	v_cmp_gt_f32_e64 s[100:101], s31, v231
	s_nop 0
	v_cndmask_b32_e64 v250, 0, 32, s[0:1]
	v_cndmask_b32_e64 v232, 0, 32, s[100:101]
	v_ldexp_f32 v249, v249, v250
	v_ldexp_f32 v231, v231, v232
	v_log_f32_e32 v249, v249
	v_log_f32_e32 v231, v231
	v_mul_f32_e32 v250, 0x3f317217, v249
	v_mul_f32_e32 v232, 0x3f317217, v231
	v_fma_f32 v250, v249, s78, -v250
	v_fma_f32 v232, v231, s78, -v232
	v_fmac_f32_e32 v250, 0x3377d1cf, v249
	v_fmac_f32_e32 v232, 0x3377d1cf, v231
	v_fmac_f32_e32 v250, 0x3f317217, v249
	v_fmac_f32_e32 v232, 0x3f317217, v231
	v_cmp_lt_f32_e64 s[88:89], |v249|, s79
	v_cndmask_b32_e64 v251, 0, v198, s[0:1]
	v_cndmask_b32_e64 v233, 0, v198, s[100:101]
	v_cndmask_b32_e64 v249, v249, v250, s[88:89]
	v_cmp_lt_f32_e64 s[88:89], |v231|, s79
	v_sub_f32_e32 v249, v249, v251
	v_sub_f32_e32 v202, v248, v249
	v_cndmask_b32_e64 v231, v231, v232, s[88:89]
	v_sub_f32_e32 v231, v231, v233
	v_sub_f32_e32 v203, v230, v231
	v_fmamk_f32 v176, v202, 0x3d800000, v173
	v_fmamk_f32 v175, v203, 0x3d800000, v172
	s_waitcnt lgkmcnt(3)
	v_fma_f32 v178, v60, v2, v69
	v_fma_f32 v179, v61, v2, v68
	v_fmac_f32_e32 v178, v62, v3
	v_fmac_f32_e32 v179, v63, v3
	v_fmac_f32_e32 v178, v64, v4
	v_fmac_f32_e32 v179, v65, v4
	v_fmac_f32_e32 v178, v66, v5
	v_fmac_f32_e32 v179, v67, v5
	s_waitcnt lgkmcnt(2)
	v_fmac_f32_e32 v178, v47, v234
	v_fmac_f32_e32 v179, v46, v234
	v_fmac_f32_e32 v178, v17, v235
	v_fmac_f32_e32 v179, v16, v235
	v_fmac_f32_e32 v178, v52, v236
	v_fmac_f32_e32 v179, v53, v236
	v_fmac_f32_e32 v178, v54, v237
	v_fmac_f32_e32 v179, v55, v237
	s_waitcnt lgkmcnt(1)
	v_fmac_f32_e32 v178, v48, v238
	v_fmac_f32_e32 v179, v49, v238
	v_fmac_f32_e32 v178, v50, v239
	v_fmac_f32_e32 v179, v51, v239
	v_fmac_f32_e32 v178, v56, v240
	v_fmac_f32_e32 v179, v57, v240
	v_fmac_f32_e32 v178, v58, v241
	v_fmac_f32_e32 v179, v59, v241
	s_waitcnt lgkmcnt(0)
	v_fmac_f32_e32 v178, v12, v244
	v_fmac_f32_e32 v179, v13, v244
	v_fmac_f32_e32 v178, v6, v245
	v_fmac_f32_e32 v179, v7, v245
	v_fmac_f32_e32 v178, v14, v246
	v_fmac_f32_e32 v179, v15, v246
	v_fmac_f32_e32 v178, v9, v247
	v_fmac_f32_e32 v179, v10, v247
	ds_read_b128 v[2:5], v19 offset:33344
	ds_read_b128 v[234:237], v19 offset:33360
	ds_read_b128 v[238:241], v19 offset:33376
	ds_read_b128 v[244:247], v19 offset:33392
	v_mul_f32_e64 v249, |v178|, s84
	v_mul_f32_e64 v231, |v179|, s84
	v_exp_f32_e32 v249, v249
	v_exp_f32_e32 v231, v231
	v_min_f32_e32 v248, 0, v178
	v_min_f32_e32 v230, 0, v179
	v_add_f32_e32 v249, 1.0, v249
	v_add_f32_e32 v231, 1.0, v231
	v_cmp_gt_f32_e64 s[0:1], s31, v249
	v_cmp_gt_f32_e64 s[100:101], s31, v231
	s_nop 0
	v_cndmask_b32_e64 v250, 0, 32, s[0:1]
	v_cndmask_b32_e64 v232, 0, 32, s[100:101]
	v_ldexp_f32 v249, v249, v250
	v_ldexp_f32 v231, v231, v232
	v_log_f32_e32 v249, v249
	v_log_f32_e32 v231, v231
	v_mul_f32_e32 v250, 0x3f317217, v249
	v_mul_f32_e32 v232, 0x3f317217, v231
	v_fma_f32 v250, v249, s78, -v250
	v_fma_f32 v232, v231, s78, -v232
	v_fmac_f32_e32 v250, 0x3377d1cf, v249
	v_fmac_f32_e32 v232, 0x3377d1cf, v231
	v_fmac_f32_e32 v250, 0x3f317217, v249
	v_fmac_f32_e32 v232, 0x3f317217, v231
	v_cmp_lt_f32_e64 s[88:89], |v249|, s79
	v_cndmask_b32_e64 v251, 0, v198, s[0:1]
	v_cndmask_b32_e64 v233, 0, v198, s[100:101]
	v_cndmask_b32_e64 v249, v249, v250, s[88:89]
	v_cmp_lt_f32_e64 s[88:89], |v231|, s79
	v_sub_f32_e32 v249, v249, v251
	v_sub_f32_e32 v206, v248, v249
	v_cndmask_b32_e64 v231, v231, v232, s[88:89]
	v_sub_f32_e32 v231, v231, v233
	v_sub_f32_e32 v207, v230, v231
	v_fmamk_f32 v179, v206, 0x3d800000, v176
	v_fmamk_f32 v178, v207, 0x3d800000, v175
	s_waitcnt lgkmcnt(3)
	v_fma_f32 v181, v60, v2, v69
	v_fma_f32 v182, v61, v2, v68
	v_fmac_f32_e32 v181, v62, v3
	v_fmac_f32_e32 v182, v63, v3
	v_fmac_f32_e32 v181, v64, v4
	v_fmac_f32_e32 v182, v65, v4
	v_fmac_f32_e32 v181, v66, v5
	v_fmac_f32_e32 v182, v67, v5
	s_waitcnt lgkmcnt(2)
	v_fmac_f32_e32 v181, v47, v234
	v_fmac_f32_e32 v182, v46, v234
	v_fmac_f32_e32 v181, v17, v235
	v_fmac_f32_e32 v182, v16, v235
	v_fmac_f32_e32 v181, v52, v236
	v_fmac_f32_e32 v182, v53, v236
	v_fmac_f32_e32 v181, v54, v237
	v_fmac_f32_e32 v182, v55, v237
	s_waitcnt lgkmcnt(1)
	v_fmac_f32_e32 v181, v48, v238
	v_fmac_f32_e32 v182, v49, v238
	v_fmac_f32_e32 v181, v50, v239
	v_fmac_f32_e32 v182, v51, v239
	v_fmac_f32_e32 v181, v56, v240
	v_fmac_f32_e32 v182, v57, v240
	v_fmac_f32_e32 v181, v58, v241
	v_fmac_f32_e32 v182, v59, v241
	s_waitcnt lgkmcnt(0)
	v_fmac_f32_e32 v181, v12, v244
	v_fmac_f32_e32 v182, v13, v244
	v_fmac_f32_e32 v181, v6, v245
	v_fmac_f32_e32 v182, v7, v245
	v_fmac_f32_e32 v181, v14, v246
	v_fmac_f32_e32 v182, v15, v246
	v_fmac_f32_e32 v181, v9, v247
	v_fmac_f32_e32 v182, v10, v247
	ds_read_b128 v[2:5], v19 offset:33408
	ds_read_b128 v[234:237], v19 offset:33424
	ds_read_b128 v[238:241], v19 offset:33440
	ds_read_b128 v[244:247], v19 offset:33456
	v_mul_f32_e64 v249, |v181|, s84
	v_mul_f32_e64 v231, |v182|, s84
	v_exp_f32_e32 v249, v249
	v_exp_f32_e32 v231, v231
	v_min_f32_e32 v248, 0, v181
	v_min_f32_e32 v230, 0, v182
	v_add_f32_e32 v249, 1.0, v249
	v_add_f32_e32 v231, 1.0, v231
	v_cmp_gt_f32_e64 s[0:1], s31, v249
	v_cmp_gt_f32_e64 s[100:101], s31, v231
	s_nop 0
	v_cndmask_b32_e64 v250, 0, 32, s[0:1]
	v_cndmask_b32_e64 v232, 0, 32, s[100:101]
	v_ldexp_f32 v249, v249, v250
	v_ldexp_f32 v231, v231, v232
	v_log_f32_e32 v249, v249
	v_log_f32_e32 v231, v231
	v_mul_f32_e32 v250, 0x3f317217, v249
	v_mul_f32_e32 v232, 0x3f317217, v231
	v_fma_f32 v250, v249, s78, -v250
	v_fma_f32 v232, v231, s78, -v232
	v_fmac_f32_e32 v250, 0x3377d1cf, v249
	v_fmac_f32_e32 v232, 0x3377d1cf, v231
	v_fmac_f32_e32 v250, 0x3f317217, v249
	v_fmac_f32_e32 v232, 0x3f317217, v231
	v_cmp_lt_f32_e64 s[88:89], |v249|, s79
	v_cndmask_b32_e64 v251, 0, v198, s[0:1]
	v_cndmask_b32_e64 v233, 0, v198, s[100:101]
	v_cndmask_b32_e64 v249, v249, v250, s[88:89]
	v_cmp_lt_f32_e64 s[88:89], |v231|, s79
	v_sub_f32_e32 v249, v249, v251
	v_sub_f32_e32 v210, v248, v249
	v_cndmask_b32_e64 v231, v231, v232, s[88:89]
	v_sub_f32_e32 v231, v231, v233
	v_sub_f32_e32 v211, v230, v231
	v_fmamk_f32 v182, v210, 0x3d800000, v179
	v_fmamk_f32 v181, v211, 0x3d800000, v178
	s_waitcnt lgkmcnt(3)
	v_fma_f32 v192, v60, v2, v69
	v_fma_f32 v193, v61, v2, v68
	v_fmac_f32_e32 v192, v62, v3
	v_fmac_f32_e32 v193, v63, v3
	v_fmac_f32_e32 v192, v64, v4
	v_fmac_f32_e32 v193, v65, v4
	v_fmac_f32_e32 v192, v66, v5
	v_fmac_f32_e32 v193, v67, v5
	s_waitcnt lgkmcnt(2)
	v_fmac_f32_e32 v192, v47, v234
	v_fmac_f32_e32 v193, v46, v234
	v_fmac_f32_e32 v192, v17, v235
	v_fmac_f32_e32 v193, v16, v235
	v_fmac_f32_e32 v192, v52, v236
	v_fmac_f32_e32 v193, v53, v236
	v_fmac_f32_e32 v192, v54, v237
	v_fmac_f32_e32 v193, v55, v237
	s_waitcnt lgkmcnt(1)
	v_fmac_f32_e32 v192, v48, v238
	v_fmac_f32_e32 v193, v49, v238
	v_fmac_f32_e32 v192, v50, v239
	v_fmac_f32_e32 v193, v51, v239
	v_fmac_f32_e32 v192, v56, v240
	v_fmac_f32_e32 v193, v57, v240
	v_fmac_f32_e32 v192, v58, v241
	v_fmac_f32_e32 v193, v59, v241
	s_waitcnt lgkmcnt(0)
	v_fmac_f32_e32 v192, v12, v244
	v_fmac_f32_e32 v193, v13, v244
	v_fmac_f32_e32 v192, v6, v245
	v_fmac_f32_e32 v193, v7, v245
	v_fmac_f32_e32 v192, v14, v246
	v_fmac_f32_e32 v193, v15, v246
	v_fmac_f32_e32 v192, v9, v247
	v_fmac_f32_e32 v193, v10, v247
	ds_read_b128 v[2:5], v19 offset:33472
	ds_read_b128 v[234:237], v19 offset:33488
	ds_read_b128 v[238:241], v19 offset:33504
	ds_read_b128 v[244:247], v19 offset:33520
	v_mul_f32_e64 v249, |v192|, s84
	v_mul_f32_e64 v231, |v193|, s84
	v_exp_f32_e32 v249, v249
	v_exp_f32_e32 v231, v231
	v_min_f32_e32 v248, 0, v192
	v_min_f32_e32 v230, 0, v193
	v_add_f32_e32 v249, 1.0, v249
	v_add_f32_e32 v231, 1.0, v231
	v_cmp_gt_f32_e64 s[0:1], s31, v249
	v_cmp_gt_f32_e64 s[100:101], s31, v231
	s_nop 0
	v_cndmask_b32_e64 v250, 0, 32, s[0:1]
	v_cndmask_b32_e64 v232, 0, 32, s[100:101]
	v_ldexp_f32 v249, v249, v250
	v_ldexp_f32 v231, v231, v232
	v_log_f32_e32 v249, v249
	v_log_f32_e32 v231, v231
	v_mul_f32_e32 v250, 0x3f317217, v249
	v_mul_f32_e32 v232, 0x3f317217, v231
	v_fma_f32 v250, v249, s78, -v250
	v_fma_f32 v232, v231, s78, -v232
	v_fmac_f32_e32 v250, 0x3377d1cf, v249
	v_fmac_f32_e32 v232, 0x3377d1cf, v231
	v_fmac_f32_e32 v250, 0x3f317217, v249
	v_fmac_f32_e32 v232, 0x3f317217, v231
	v_cmp_lt_f32_e64 s[88:89], |v249|, s79
	v_cndmask_b32_e64 v251, 0, v198, s[0:1]
	v_cndmask_b32_e64 v233, 0, v198, s[100:101]
	v_cndmask_b32_e64 v249, v249, v250, s[88:89]
	v_cmp_lt_f32_e64 s[88:89], |v231|, s79
	v_sub_f32_e32 v249, v249, v251
	v_sub_f32_e32 v214, v248, v249
	v_cndmask_b32_e64 v231, v231, v232, s[88:89]
	v_sub_f32_e32 v231, v231, v233
	v_sub_f32_e32 v217, v230, v231
	v_fmamk_f32 v201, v214, 0x3d800000, v182
	v_fmamk_f32 v200, v217, 0x3d800000, v181
	s_waitcnt lgkmcnt(3)
	v_fma_f32 v192, v60, v2, v69
	v_fma_f32 v193, v61, v2, v68
	v_fmac_f32_e32 v192, v62, v3
	v_fmac_f32_e32 v193, v63, v3
	v_fmac_f32_e32 v192, v64, v4
	v_fmac_f32_e32 v193, v65, v4
	v_fmac_f32_e32 v192, v66, v5
	v_fmac_f32_e32 v193, v67, v5
	s_waitcnt lgkmcnt(2)
	v_fmac_f32_e32 v192, v47, v234
	v_fmac_f32_e32 v193, v46, v234
	v_fmac_f32_e32 v192, v17, v235
	v_fmac_f32_e32 v193, v16, v235
	v_fmac_f32_e32 v192, v52, v236
	v_fmac_f32_e32 v193, v53, v236
	v_fmac_f32_e32 v192, v54, v237
	v_fmac_f32_e32 v193, v55, v237
	s_waitcnt lgkmcnt(1)
	v_fmac_f32_e32 v192, v48, v238
	v_fmac_f32_e32 v193, v49, v238
	v_fmac_f32_e32 v192, v50, v239
	v_fmac_f32_e32 v193, v51, v239
	v_fmac_f32_e32 v192, v56, v240
	v_fmac_f32_e32 v193, v57, v240
	v_fmac_f32_e32 v192, v58, v241
	v_fmac_f32_e32 v193, v59, v241
	s_waitcnt lgkmcnt(0)
	v_fmac_f32_e32 v192, v12, v244
	v_fmac_f32_e32 v193, v13, v244
	v_fmac_f32_e32 v192, v6, v245
	v_fmac_f32_e32 v193, v7, v245
	v_fmac_f32_e32 v192, v14, v246
	v_fmac_f32_e32 v193, v15, v246
	v_fmac_f32_e32 v192, v9, v247
	v_fmac_f32_e32 v193, v10, v247
	ds_read_b128 v[2:5], v19 offset:33536
	ds_read_b128 v[234:237], v19 offset:33552
	ds_read_b128 v[238:241], v19 offset:33568
	ds_read_b128 v[244:247], v19 offset:33584
	v_mul_f32_e64 v249, |v192|, s84
	v_mul_f32_e64 v231, |v193|, s84
	v_exp_f32_e32 v249, v249
	v_exp_f32_e32 v231, v231
	v_min_f32_e32 v248, 0, v192
	v_min_f32_e32 v230, 0, v193
	v_add_f32_e32 v249, 1.0, v249
	v_add_f32_e32 v231, 1.0, v231
	v_cmp_gt_f32_e64 s[0:1], s31, v249
	v_cmp_gt_f32_e64 s[100:101], s31, v231
	s_nop 0
	v_cndmask_b32_e64 v250, 0, 32, s[0:1]
	v_cndmask_b32_e64 v232, 0, 32, s[100:101]
	v_ldexp_f32 v249, v249, v250
	v_ldexp_f32 v231, v231, v232
	v_log_f32_e32 v249, v249
	v_log_f32_e32 v231, v231
	v_mul_f32_e32 v250, 0x3f317217, v249
	v_mul_f32_e32 v232, 0x3f317217, v231
	v_fma_f32 v250, v249, s78, -v250
	v_fma_f32 v232, v231, s78, -v232
	v_fmac_f32_e32 v250, 0x3377d1cf, v249
	v_fmac_f32_e32 v232, 0x3377d1cf, v231
	v_fmac_f32_e32 v250, 0x3f317217, v249
	v_fmac_f32_e32 v232, 0x3f317217, v231
	v_cmp_lt_f32_e64 s[88:89], |v249|, s79
	v_cndmask_b32_e64 v251, 0, v198, s[0:1]
	v_cndmask_b32_e64 v233, 0, v198, s[100:101]
	v_cndmask_b32_e64 v249, v249, v250, s[88:89]
	v_cmp_lt_f32_e64 s[88:89], |v231|, s79
	v_sub_f32_e32 v249, v249, v251
	v_sub_f32_e32 v218, v248, v249
	v_cndmask_b32_e64 v231, v231, v232, s[88:89]
	v_sub_f32_e32 v231, v231, v233
	v_sub_f32_e32 v223, v230, v231
	v_fmamk_f32 v205, v218, 0x3d800000, v201
	v_fmamk_f32 v204, v223, 0x3d800000, v200
	s_waitcnt lgkmcnt(3)
	v_fma_f32 v192, v60, v2, v69
	v_fma_f32 v193, v61, v2, v68
	v_fmac_f32_e32 v192, v62, v3
	v_fmac_f32_e32 v193, v63, v3
	v_fmac_f32_e32 v192, v64, v4
	v_fmac_f32_e32 v193, v65, v4
	v_fmac_f32_e32 v192, v66, v5
	v_fmac_f32_e32 v193, v67, v5
	s_waitcnt lgkmcnt(2)
	v_fmac_f32_e32 v192, v47, v234
	v_fmac_f32_e32 v193, v46, v234
	v_fmac_f32_e32 v192, v17, v235
	v_fmac_f32_e32 v193, v16, v235
	v_fmac_f32_e32 v192, v52, v236
	v_fmac_f32_e32 v193, v53, v236
	v_fmac_f32_e32 v192, v54, v237
	v_fmac_f32_e32 v193, v55, v237
	s_waitcnt lgkmcnt(1)
	v_fmac_f32_e32 v192, v48, v238
	v_fmac_f32_e32 v193, v49, v238
	v_fmac_f32_e32 v192, v50, v239
	v_fmac_f32_e32 v193, v51, v239
	v_fmac_f32_e32 v192, v56, v240
	v_fmac_f32_e32 v193, v57, v240
	v_fmac_f32_e32 v192, v58, v241
	v_fmac_f32_e32 v193, v59, v241
	s_waitcnt lgkmcnt(0)
	v_fmac_f32_e32 v192, v12, v244
	v_fmac_f32_e32 v193, v13, v244
	v_fmac_f32_e32 v192, v6, v245
	v_fmac_f32_e32 v193, v7, v245
	v_fmac_f32_e32 v192, v14, v246
	v_fmac_f32_e32 v193, v15, v246
	v_fmac_f32_e32 v192, v9, v247
	v_fmac_f32_e32 v193, v10, v247
	ds_read_b128 v[2:5], v19 offset:33600
	ds_read_b128 v[234:237], v19 offset:33616
	ds_read_b128 v[238:241], v19 offset:33632
	ds_read_b128 v[244:247], v19 offset:33648
	v_mul_f32_e64 v249, |v192|, s84
	v_mul_f32_e64 v231, |v193|, s84
	v_exp_f32_e32 v249, v249
	v_exp_f32_e32 v231, v231
	v_min_f32_e32 v248, 0, v192
	v_min_f32_e32 v230, 0, v193
	v_add_f32_e32 v249, 1.0, v249
	v_add_f32_e32 v231, 1.0, v231
	v_cmp_gt_f32_e64 s[0:1], s31, v249
	v_cmp_gt_f32_e64 s[100:101], s31, v231
	s_nop 0
	v_cndmask_b32_e64 v250, 0, 32, s[0:1]
	v_cndmask_b32_e64 v232, 0, 32, s[100:101]
	v_ldexp_f32 v249, v249, v250
	v_ldexp_f32 v231, v231, v232
	v_log_f32_e32 v249, v249
	v_log_f32_e32 v231, v231
	v_mul_f32_e32 v250, 0x3f317217, v249
	v_mul_f32_e32 v232, 0x3f317217, v231
	v_fma_f32 v250, v249, s78, -v250
	v_fma_f32 v232, v231, s78, -v232
	v_fmac_f32_e32 v250, 0x3377d1cf, v249
	v_fmac_f32_e32 v232, 0x3377d1cf, v231
	v_fmac_f32_e32 v250, 0x3f317217, v249
	v_fmac_f32_e32 v232, 0x3f317217, v231
	v_cmp_lt_f32_e64 s[88:89], |v249|, s79
	v_cndmask_b32_e64 v251, 0, v198, s[0:1]
	v_cndmask_b32_e64 v233, 0, v198, s[100:101]
	v_cndmask_b32_e64 v249, v249, v250, s[88:89]
	v_cmp_lt_f32_e64 s[88:89], |v231|, s79
	v_sub_f32_e32 v249, v249, v251
	v_sub_f32_e32 v224, v248, v249
	v_cndmask_b32_e64 v231, v231, v232, s[88:89]
	v_sub_f32_e32 v231, v231, v233
	v_sub_f32_e32 v225, v230, v231
	v_fmamk_f32 v209, v224, 0x3d800000, v205
	v_fmamk_f32 v208, v225, 0x3d800000, v204
	s_waitcnt lgkmcnt(3)
	v_fma_f32 v192, v60, v2, v69
	v_fma_f32 v193, v61, v2, v68
	v_fmac_f32_e32 v192, v62, v3
	v_fmac_f32_e32 v193, v63, v3
	v_fmac_f32_e32 v192, v64, v4
	v_fmac_f32_e32 v193, v65, v4
	v_fmac_f32_e32 v192, v66, v5
	v_fmac_f32_e32 v193, v67, v5
	s_waitcnt lgkmcnt(2)
	v_fmac_f32_e32 v192, v47, v234
	v_fmac_f32_e32 v193, v46, v234
	v_fmac_f32_e32 v192, v17, v235
	v_fmac_f32_e32 v193, v16, v235
	v_fmac_f32_e32 v192, v52, v236
	v_fmac_f32_e32 v193, v53, v236
	v_fmac_f32_e32 v192, v54, v237
	v_fmac_f32_e32 v193, v55, v237
	s_waitcnt lgkmcnt(1)
	v_fmac_f32_e32 v192, v48, v238
	v_fmac_f32_e32 v193, v49, v238
	v_fmac_f32_e32 v192, v50, v239
	v_fmac_f32_e32 v193, v51, v239
	v_fmac_f32_e32 v192, v56, v240
	v_fmac_f32_e32 v193, v57, v240
	v_fmac_f32_e32 v192, v58, v241
	v_fmac_f32_e32 v193, v59, v241
	s_waitcnt lgkmcnt(0)
	v_fmac_f32_e32 v192, v12, v244
	v_fmac_f32_e32 v193, v13, v244
	v_fmac_f32_e32 v192, v6, v245
	v_fmac_f32_e32 v193, v7, v245
	v_fmac_f32_e32 v192, v14, v246
	v_fmac_f32_e32 v193, v15, v246
	v_fmac_f32_e32 v192, v9, v247
	v_fmac_f32_e32 v193, v10, v247
	ds_read_b128 v[2:5], v19 offset:33664
	ds_read_b128 v[234:237], v19 offset:33680
	ds_read_b128 v[238:241], v19 offset:33696
	ds_read_b128 v[244:247], v19 offset:33712
	v_mul_f32_e64 v249, |v192|, s84
	v_mul_f32_e64 v231, |v193|, s84
	v_exp_f32_e32 v249, v249
	v_exp_f32_e32 v231, v231
	v_min_f32_e32 v248, 0, v192
	v_min_f32_e32 v230, 0, v193
	v_add_f32_e32 v249, 1.0, v249
	v_add_f32_e32 v231, 1.0, v231
	v_cmp_gt_f32_e64 s[0:1], s31, v249
	v_cmp_gt_f32_e64 s[100:101], s31, v231
	s_nop 0
	v_cndmask_b32_e64 v250, 0, 32, s[0:1]
	v_cndmask_b32_e64 v232, 0, 32, s[100:101]
	v_ldexp_f32 v249, v249, v250
	v_ldexp_f32 v231, v231, v232
	v_log_f32_e32 v249, v249
	v_log_f32_e32 v231, v231
	v_mul_f32_e32 v250, 0x3f317217, v249
	v_mul_f32_e32 v232, 0x3f317217, v231
	v_fma_f32 v250, v249, s78, -v250
	v_fma_f32 v232, v231, s78, -v232
	v_fmac_f32_e32 v250, 0x3377d1cf, v249
	v_fmac_f32_e32 v232, 0x3377d1cf, v231
	v_fmac_f32_e32 v250, 0x3f317217, v249
	v_fmac_f32_e32 v232, 0x3f317217, v231
	v_cmp_lt_f32_e64 s[88:89], |v249|, s79
	v_cndmask_b32_e64 v251, 0, v198, s[0:1]
	v_cndmask_b32_e64 v233, 0, v198, s[100:101]
	v_cndmask_b32_e64 v249, v249, v250, s[88:89]
	v_cmp_lt_f32_e64 s[88:89], |v231|, s79
	v_sub_f32_e32 v249, v249, v251
	v_sub_f32_e32 v226, v248, v249
	v_cndmask_b32_e64 v231, v231, v232, s[88:89]
	v_sub_f32_e32 v231, v231, v233
	v_sub_f32_e32 v227, v230, v231
	v_fmamk_f32 v213, v226, 0x3d800000, v209
	v_fmamk_f32 v212, v227, 0x3d800000, v208
	s_waitcnt lgkmcnt(3)
	v_fma_f32 v192, v60, v2, v69
	v_fma_f32 v193, v61, v2, v68
	v_fmac_f32_e32 v192, v62, v3
	v_fmac_f32_e32 v193, v63, v3
	v_fmac_f32_e32 v192, v64, v4
	v_fmac_f32_e32 v193, v65, v4
	v_fmac_f32_e32 v192, v66, v5
	v_fmac_f32_e32 v193, v67, v5
	s_waitcnt lgkmcnt(2)
	v_fmac_f32_e32 v192, v47, v234
	v_fmac_f32_e32 v193, v46, v234
	v_fmac_f32_e32 v192, v17, v235
	v_fmac_f32_e32 v193, v16, v235
	v_fmac_f32_e32 v192, v52, v236
	v_fmac_f32_e32 v193, v53, v236
	v_fmac_f32_e32 v192, v54, v237
	v_fmac_f32_e32 v193, v55, v237
	s_waitcnt lgkmcnt(1)
	v_fmac_f32_e32 v192, v48, v238
	v_fmac_f32_e32 v193, v49, v238
	v_fmac_f32_e32 v192, v50, v239
	v_fmac_f32_e32 v193, v51, v239
	v_fmac_f32_e32 v192, v56, v240
	v_fmac_f32_e32 v193, v57, v240
	v_fmac_f32_e32 v192, v58, v241
	v_fmac_f32_e32 v193, v59, v241
	s_waitcnt lgkmcnt(0)
	v_fmac_f32_e32 v192, v12, v244
	v_fmac_f32_e32 v193, v13, v244
	v_fmac_f32_e32 v192, v6, v245
	v_fmac_f32_e32 v193, v7, v245
	v_fmac_f32_e32 v192, v14, v246
	v_fmac_f32_e32 v193, v15, v246
	v_fmac_f32_e32 v192, v9, v247
	v_fmac_f32_e32 v193, v10, v247
	v_mul_f32_e64 v249, |v192|, s84
	v_mul_f32_e64 v231, |v193|, s84
	v_exp_f32_e32 v249, v249
	v_exp_f32_e32 v231, v231
	v_min_f32_e32 v248, 0, v192
	v_min_f32_e32 v230, 0, v193
	v_add_f32_e32 v249, 1.0, v249
	v_add_f32_e32 v231, 1.0, v231
	v_cmp_gt_f32_e64 s[0:1], s31, v249
	v_cmp_gt_f32_e64 s[100:101], s31, v231
	s_nop 0
	v_cndmask_b32_e64 v250, 0, 32, s[0:1]
	v_cndmask_b32_e64 v232, 0, 32, s[100:101]
	v_ldexp_f32 v249, v249, v250
	v_ldexp_f32 v231, v231, v232
	v_log_f32_e32 v249, v249
	v_log_f32_e32 v231, v231
	v_mul_f32_e32 v250, 0x3f317217, v249
	v_mul_f32_e32 v232, 0x3f317217, v231
	v_fma_f32 v250, v249, s78, -v250
	v_fma_f32 v232, v231, s78, -v232
	v_fmac_f32_e32 v250, 0x3377d1cf, v249
	v_fmac_f32_e32 v232, 0x3377d1cf, v231
	v_fmac_f32_e32 v250, 0x3f317217, v249
	v_fmac_f32_e32 v232, 0x3f317217, v231
	v_cmp_lt_f32_e64 s[88:89], |v249|, s79
	v_cndmask_b32_e64 v251, 0, v198, s[0:1]
	v_cndmask_b32_e64 v233, 0, v198, s[100:101]
	v_cndmask_b32_e64 v249, v249, v250, s[88:89]
	v_cmp_lt_f32_e64 s[88:89], |v231|, s79
	v_sub_f32_e32 v249, v249, v251
	v_sub_f32_e32 v228, v248, v249
	v_cndmask_b32_e64 v231, v231, v232, s[88:89]
	v_sub_f32_e32 v231, v231, v233
	v_sub_f32_e32 v229, v230, v231
	v_fmamk_f32 v216, v228, 0x3d800000, v213
	v_fmamk_f32 v215, v229, 0x3d800000, v212
	ds_read_b128 v[2:5], v19 offset:33728
	s_waitcnt lgkmcnt(0)
	v_fmac_f32_e32 v69, v60, v2
	v_fmac_f32_e32 v68, v61, v2
	v_fmac_f32_e32 v69, v62, v3
	v_fmac_f32_e32 v68, v63, v3
	v_fmac_f32_e32 v69, v64, v4
	v_fmac_f32_e32 v68, v65, v4
	v_fmac_f32_e32 v69, v66, v5
	v_fmac_f32_e32 v68, v67, v5
	ds_read_b128 v[2:5], v19 offset:33744
	s_waitcnt lgkmcnt(0)
	v_fmac_f32_e32 v69, v47, v2
	v_fmac_f32_e32 v68, v46, v2
	v_fmac_f32_e32 v69, v17, v3
	v_fmac_f32_e32 v68, v16, v3
	v_fmac_f32_e32 v69, v52, v4
	v_fmac_f32_e32 v68, v53, v4
	v_fmac_f32_e32 v69, v54, v5
	v_fmac_f32_e32 v68, v55, v5
	ds_read_b128 v[2:5], v19 offset:33760
	v_mov_b64_e32 v[46:47], s[58:59]
	s_waitcnt lgkmcnt(0)
	v_fmac_f32_e32 v69, v48, v2
	v_fmac_f32_e32 v68, v49, v2
	v_fmac_f32_e32 v69, v50, v3
	v_fmac_f32_e32 v68, v51, v3
	v_fmac_f32_e32 v69, v56, v4
	v_fmac_f32_e32 v68, v57, v4
	v_fmac_f32_e32 v69, v58, v5
	v_fmac_f32_e32 v68, v59, v5
	ds_read_b128 v[2:5], v19 offset:33776
	s_waitcnt lgkmcnt(0)
	v_fmac_f32_e32 v69, v12, v2
	v_fmac_f32_e32 v69, v6, v3
	v_fmac_f32_e32 v69, v14, v4
	v_fmac_f32_e32 v68, v13, v2
	v_fmac_f32_e32 v69, v9, v5
	v_fmac_f32_e32 v68, v7, v3
	v_mul_f32_e64 v3, |v69|, s84
	v_exp_f32_e32 v3, v3
	v_fmac_f32_e32 v68, v15, v4
	v_fmac_f32_e32 v68, v10, v5
	v_min_f32_e32 v2, 0, v69
	v_add_f32_e32 v3, 1.0, v3
	v_cmp_gt_f32_e64 s[0:1], s31, v3
	s_nop 1
	v_cndmask_b32_e64 v4, 0, 32, s[0:1]
	v_ldexp_f32 v3, v3, v4
	v_log_f32_e32 v3, v3
	s_nop 0
	v_mul_f32_e32 v4, 0x3f317217, v3
	v_fma_f32 v4, v3, s78, -v4
	v_fmac_f32_e32 v4, 0x3377d1cf, v3
	v_fmac_f32_e32 v4, 0x3f317217, v3
	v_cmp_lt_f32_e64 s[88:89], |v3|, s79
	s_nop 1
	v_cndmask_b32_e64 v3, v3, v4, s[88:89]
	v_cndmask_b32_e64 v4, 0, v198, s[0:1]
	v_sub_f32_e32 v3, v3, v4
	v_sub_f32_e32 v9, v2, v3
	v_mul_f32_e64 v3, |v68|, s84
	v_exp_f32_e32 v3, v3
	v_min_f32_e32 v2, 0, v68
	v_fmamk_f32 v220, v9, 0x3d800000, v216
	v_add_f32_e32 v3, 1.0, v3
	v_cmp_gt_f32_e64 s[0:1], s31, v3
	s_nop 1
	v_cndmask_b32_e64 v4, 0, 32, s[0:1]
	v_ldexp_f32 v3, v3, v4
	v_log_f32_e32 v3, v3
	s_nop 0
	v_mul_f32_e32 v4, 0x3f317217, v3
	v_fma_f32 v4, v3, s78, -v4
	v_fmac_f32_e32 v4, 0x3377d1cf, v3
	v_fmac_f32_e32 v4, 0x3f317217, v3
	v_cmp_lt_f32_e64 s[88:89], |v3|, s79
	s_nop 1
	v_cndmask_b32_e64 v3, v3, v4, s[88:89]
	v_cndmask_b32_e64 v4, 0, v198, s[0:1]
	v_sub_f32_e32 v3, v3, v4
	v_sub_f32_e32 v14, v2, v3
	v_fmamk_f32 v219, v14, 0x3d800000, v215
	ds_write2st64_b32 v23, v220, v219 offset0:144 offset1:145
	s_waitcnt lgkmcnt(0)
	s_barrier
	ds_read2st64_b32 v[2:3], v22 offset0:144 offset1:145
	ds_read2st64_b32 v[6:7], v22 offset0:146 offset1:147
	ds_read2st64_b32 v[4:5], v22 offset0:148 offset1:149
	s_waitcnt lgkmcnt(2)
	v_add_f32_e32 v10, 0, v2
	v_add_f32_e32 v13, 0, v3
	s_waitcnt lgkmcnt(1)
	v_add_f32_e32 v2, v10, v6
	v_add_f32_e32 v3, v13, v7
	s_waitcnt lgkmcnt(0)
	v_add_f32_e32 v12, v2, v4
	v_add_f32_e32 v15, v3, v5
	ds_read2st64_b32 v[2:3], v22 offset0:150 offset1:151
	s_waitcnt lgkmcnt(0)
	v_add_f32_e32 v12, v12, v2
	v_add_f32_e32 v15, v15, v3
	v_mul_f32_e32 v12, 0x3fb8aa3b, v12
	v_exp_f32_e32 v221, v12
	v_mul_f32_e32 v12, 0x3fb8aa3b, v15
	v_exp_f32_e32 v222, v12
	s_and_saveexec_b64 s[0:1], s[6:7]
	s_cbranch_execz .LBB0_224
	s_ashr_i32 s5, s58, 31
	s_mov_b32 s4, s58
	v_mov_b64_e32 v[46:47], s[4:5]
	global_store_dword v[36:37], v221, off
	global_store_dword v[36:37], v222, off offset:256
	s_branch .LBB0_224
